# D unit: static priority raise (s_setprio 2) for waves 4-7 so the two waves of a SIMD run their MFMA and VALU phases out of step
# speedup vs baseline: 1.0082x; 1.0082x over previous
; __device__ __forceinline__ unsigned xb_xcc_id() { return (unsigned)__builtin_amdgcn_s_getreg((3 << 11) | 20) & 0xFu; }
; __global__ void __launch_bounds__(NT, 2) fwd(Args args) {
;     ...
;         for (int r2 = 0; r2 < ((SEQ_P2A & 2) ? 2 : 1); ++r2) for (;;) {
;             __syncthreads();
;             if (tid == 0) { const unsigned myx = xb_xcc_id() & 7u; int got = -1;
;                 for (unsigned k = 0; k < 8u && got < 0; ++k) { const unsigned x = (myx + k) & 7u;
;                     const unsigned v = __hip_atomic_fetch_add(ctl + CW_QD + ((pass * 2 + r2) * 8 + x) * 64, 1u, RLX_AGENT); if (v < 32u) got = (int)(x * 32u + v); }
;                 *slot = got; }
.LBB0_746:
	s_setprio 0
	s_waitcnt vmcnt(0)
	s_barrier
	s_and_saveexec_b64 s[6:7], s[56:57]
	s_cbranch_execz .LBB0_752
	s_mov_b32 s1, 0
	s_mov_b64 s[8:9], 0
	s_getreg_b32 s0, hwreg(HW_REG_XCC_ID, 0, 4)
	s_branch .LBB0_749

; #define LAS __attribute__((address_space(3)))
; DI float fexp2(float x) { return __builtin_amdgcn_exp2f(x); }
; DI void unit_dilated2(int u, const bf16* __restrict__ Q, const bf16* __restrict__ K, const bf16* __restrict__ V, const bf16* __restrict__ G, bf16* __restrict__ MIX, LAS unsigned char* lds, int tid, int lane, int wave) {
;     asm volatile("" : "+v"(lane), "+v"(tid));
;     const int bh = u >> 4, blk = u & 15, b = bh >> 3, h = bh & 7, T0 = blk * 512;
;     const int qq = lane & 31, hh = lane >> 5;
;     LAS unsigned char* kst = lds + DL_STAGE + wave * 8192; LAS unsigned char* vst = kst + 4096;
;     LAS float* lseb = (LAS float*)(lds + DL_LSE);
;     const float slope2 = fexp2(-(float)(h + 1)) * LOG2E;
;     DilWT cw = dil_wt(0, wave, b, h, T0, qq, slope2);
;     bf16x8 qf[4];
; #pragma unroll
;     for (int st = 0; st < 4; ++st) qf[st] = *(const bf16x8*)(Q + cw.qrow * 512 + h * 64 + 16 * st + 8 * hh);
;     v4u kr[4], vr[4];
;     dil_load(kr, vr, K, V, cw.rb0 + (long)(32 * 4) * cw.gstride, cw.gstride, lane);
; __global__ void __launch_bounds__(NT, 2) fwd(Args args) {
;     ...
;             const int u = __builtin_amdgcn_readfirstlane(*slot); if (u < 0) break;
;             unit_dilated2(u, QB, KB, VB, GB, MIX, lds, tid, lane, wave); }
.LBB0_752:
	s_or_b64 exec, exec, s[6:7]
	v_mov_b32_e32 v3, s49
	s_waitcnt lgkmcnt(0)
	s_barrier
	ds_read_b32 v3, v3
	s_waitcnt lgkmcnt(0)
	v_readfirstlane_b32 s0, v3
	s_cmp_lt_i32 s0, 0
	s_cbranch_scc1 .LBB0_786
	s_cmp_lt_u32 s33, 4
	s_cbranch_scc1 .Ldprio_lo
	s_setprio 2
.Ldprio_lo:
	s_lshr_b32 s38, s0, 7
	s_bfe_u32 s2, s0, 0x30004
	s_lshl_b32 s0, s0, 9
	s_and_b32 s34, s0, 0x1e00
	s_or_b32 s6, s34, s41
	s_sub_i32 s0, 0x80, s6
	s_lshl_b64 s[12:13], s[38:39], 13
	s_lshr_b32 s7, s0, 5
	s_add_i32 s0, s6, 0xffffff80
	s_add_i32 s3, s2, 1
	s_or_b32 s10, s12, s34
	s_ashr_i32 s1, s0, 31
	v_mov_b32_e32 v3, v182
	v_mov_b32_e32 v227, v0
	s_add_u32 s8, s12, s40
	s_addc_u32 s9, s13, 0
	v_and_b32_e32 v228, 31, v3
	v_or_b32_e32 v4, s41, v228
	s_add_u32 s0, s8, s0
	v_add_u32_e32 v184, s40, v4
	s_mov_b32 s11, s13
	v_mov_b32_e32 v185, v2
	s_addc_u32 s1, s9, s1
	s_lshl_b32 s14, s2, 6
	s_lshl_b32 s38, s2, 7
	v_ashrrev_i32_e32 v14, 5, v3
	v_lshl_add_u64 v[4:5], s[10:11], 0, v[184:185]
	s_cmpk_lt_u32 s6, 0x80
	v_lshlrev_b64 v[4:5], 10, v[4:5]
	v_lshlrev_b32_e32 v6, 3, v14
	s_cselect_b32 s47, s7, 0
	s_lshl_b64 s[16:17], s[0:1], 9
	v_lshl_add_u64 v[4:5], s[78:79], 0, v[4:5]
	v_ashrrev_i32_e32 v7, 31, v6
	s_or_b32 s16, s16, s14
	v_lshl_add_u64 v[4:5], v[4:5], 0, s[38:39]
	v_lshlrev_b64 v[8:9], 1, v[6:7]
	s_add_u32 s0, s16, 0x10000
	v_ashrrev_i32_e32 v186, 3, v3
	v_lshlrev_b32_e32 v7, 3, v3
	v_lshl_add_u64 v[4:5], v[4:5], 0, v[8:9]
	s_addc_u32 s1, s17, 0
	v_and_b32_e32 v188, 56, v7
	v_ashrrev_i32_e32 v187, 31, v186
	global_load_dwordx4 v[114:117], v[4:5], off
	global_load_dwordx4 v[118:121], v[4:5], off offset:32
	global_load_dwordx4 v[122:125], v[4:5], off offset:64
	global_load_dwordx4 v[130:133], v[4:5], off offset:96
	v_or_b32_e32 v4, s0, v188
	v_mov_b32_e32 v5, s1
	v_lshlrev_b64 v[10:11], 9, v[186:187]
	v_lshl_add_u64 v[10:11], v[4:5], 0, v[10:11]
	v_lshlrev_b64 v[10:11], 1, v[10:11]
	v_add_u32_e32 v190, 8, v186
	v_lshl_add_u64 v[12:13], s[76:77], 0, v[10:11]
	v_lshl_add_u64 v[10:11], s[80:81], 0, v[10:11]
	v_ashrrev_i32_e32 v191, 31, v190
	global_load_dwordx4 v[126:129], v[12:13], off
	global_load_dwordx4 v[134:137], v[10:11], off
	v_lshlrev_b64 v[10:11], 9, v[190:191]
	v_lshl_add_u64 v[10:11], v[4:5], 0, v[10:11]
	v_lshlrev_b64 v[10:11], 1, v[10:11]
	v_add_u32_e32 v192, 16, v186
	v_lshl_add_u64 v[12:13], s[76:77], 0, v[10:11]
	v_lshl_add_u64 v[10:11], s[80:81], 0, v[10:11]
	v_ashrrev_i32_e32 v193, 31, v192
	global_load_dwordx4 v[138:141], v[12:13], off
	global_load_dwordx4 v[142:145], v[10:11], off
	v_lshlrev_b64 v[10:11], 9, v[192:193]
	v_lshl_add_u64 v[10:11], v[4:5], 0, v[10:11]
	v_lshlrev_b64 v[10:11], 1, v[10:11]
	v_add_u32_e32 v194, 24, v186
	v_lshl_add_u64 v[12:13], s[76:77], 0, v[10:11]
	v_lshl_add_u64 v[10:11], s[80:81], 0, v[10:11]
	v_ashrrev_i32_e32 v195, 31, v194
	global_load_dwordx4 v[146:149], v[12:13], off
	global_load_dwordx4 v[150:153], v[10:11], off
	v_lshlrev_b64 v[10:11], 9, v[194:195]
	v_lshl_add_u64 v[4:5], v[4:5], 0, v[10:11]
	v_lshlrev_b64 v[4:5], 1, v[4:5]
	v_lshl_add_u64 v[10:11], s[76:77], 0, v[4:5]
	v_lshl_add_u64 v[4:5], s[80:81], 0, v[4:5]
	global_load_dwordx4 v[154:157], v[10:11], off
	global_load_dwordx4 v[158:161], v[4:5], off
	v_cvt_f32_ubyte0_e32 v4, s3
	v_exp_f32_e64 v4, -v4
	v_xor_b32_e32 v5, v186, v3
	v_lshlrev_b32_e32 v5, 4, v5
	s_add_u32 s0, s78, s38
	v_mul_f32_e32 v229, 0x3fb8aa3b, v4
	v_lshlrev_b32_e32 v4, 7, v186
	v_and_or_b32 v4, v5, s50, v4
	v_lshlrev_b32_e32 v5, 2, v14
	v_lshrrev_b32_e32 v13, 2, v3
	s_addc_u32 s1, s79, 0
	v_and_or_b32 v13, v13, 3, v5
	v_lshl_add_u64 v[196:197], s[0:1], 0, v[8:9]
	v_bitop3_b32 v9, v14, v3, 7 bitop3:0x78
	v_add_u32_e32 v10, 2, v14
	v_add_u32_e32 v11, 4, v14
	v_add_u32_e32 v12, 6, v14
	v_lshlrev_b32_e32 v14, 7, v13
	v_and_b32_e32 v7, 8, v7
	v_add3_u32 v7, s73, v14, v7
	v_lshrrev_b32_e32 v14, 3, v3
	v_sub_u32_e32 v230, v5, v228
	v_and_b32_e32 v14, 2, v14
	v_bfe_u32 v15, v3, 1, 1
; #define LAS __attribute__((address_space(3)))
; DI s16x4 vtr(LAS const unsigned char* p) { return __builtin_bit_cast(s16x4, __builtin_amdgcn_ds_read_tr16_b64_v4i16((LAS v4i16_t*)p)); }
; #define MFMA32(a, b, c) __builtin_amdgcn_mfma_f32_32x32x16_bf16((a), (b), (c), 0, 0, 0)
; template <bool MASKED>
; DI void attn_tile_sw(int MODE, LAS const unsigned char* kst, LAS const unsigned char* vst, const bf16x8 (&qf)[4], float bstep, float ca, int lane, f32x16& o0, f32x16& o1, float& m, float& l) {
;     ...
;     f32x16 s; { const float sb = bstep * (float)(4 * hh - qq);
; #pragma unroll
;         for (int i = 0; i < 16; ++i) s[i] = bstep * (float)((i & 3) + 8 * (i >> 2)) + sb; }
;     {   bf16x8 kf[4];
; #pragma unroll
;         for (int st = 0; st < 4; ++st) kf[st] = *(LAS const bf16x8*)(kst + qq * 128 + (((2 * st + hh) ^ (qq & 7)) << 4));
; #pragma unroll
;         for (int st = 0; st < 4; ++st) s = MFMA32(kf[st], qf[st], s); }
;     const int q4 = (lane & 15) >> 2, p = lane & 3, blk = (lane >> 4) & 1, x = 4 * hh + q4;
;     LAS const unsigned char* vb = vst + x * 128 + 8 * (p & 1);
;     const int ch0 = ((2 * blk + (p >> 1)) ^ x) << 4, ch1 = ((4 + 2 * blk + (p >> 1)) ^ x) << 4;
;     const s16x4 va0 = vtr(vb + ch0), va1 = vtr(vb + 8 * 128 + ch0), vb0 = vtr(vb + ch1), vb1 = vtr(vb + 8 * 128 + ch1);
;     const s16x4 vc0 = vtr(vb + 16 * 128 + ch0), vc1 = vtr(vb + 24 * 128 + ch0), vd0 = vtr(vb + 16 * 128 + ch1), vd1 = vtr(vb + 24 * 128 + ch1);
;     if (MASKED) { const int dq = (MODE == 1) ? (qq - 4 * hh) : (4 * hh - qq);
; #pragma unroll
;         for (int r = 0; r < 16; ++r) { const int kq = (r & 3) + 8 * (r >> 2); s[r] = (((MODE == 1) ? kq : -kq) < dq) ? NEG : s[r]; } }
	v_cvt_f32_i32_e32 v231, v230
	v_or_b32_e32 v16, v14, v15
	v_bitop3_b32 v10, v10, v3, 7 bitop3:0x78
	v_bitop3_b32 v11, v11, v3, 7 bitop3:0x78
	v_bitop3_b32 v12, v12, v3, 7 bitop3:0x78
	v_bitop3_b32 v14, v14, v13, v15 bitop3:0x36
	v_bitop3_b32 v13, v16, v13, 4 bitop3:0x36
	v_lshl_add_u32 v8, v228, 7, s73
	v_lshlrev_b32_e32 v9, 4, v9
	v_lshlrev_b32_e32 v10, 4, v10
	v_lshlrev_b32_e32 v11, 4, v11
	v_lshlrev_b32_e32 v12, 4, v12
	v_lshlrev_b32_e32 v14, 4, v14
	v_lshlrev_b32_e32 v13, 4, v13
	s_mov_b32 s15, s39
	s_mov_b32 s44, 0
	v_mov_b32_e32 v189, v2
	v_sub_u32_e32 v232, v228, v5
	v_add_u32_e32 v233, 0, v6
	v_cmp_gt_u32_e64 s[6:7], 32, v3
	s_mov_b64 s[18:19], 0x200
	v_add_u32_e32 v234, s73, v4
	v_add_u32_e32 v235, v8, v9
	v_add_u32_e32 v236, v8, v10
	v_add_u32_e32 v237, v8, v11
	v_add_u32_e32 v238, v8, v12
	v_add_u32_e32 v239, v7, v14
	v_add_u32_e32 v240, v7, v13
	v_mov_b32_e32 v199, v229
	v_mov_b32_e32 v18, v231
	v_add_f32_e32 v19, 1.0, v231
	v_add_f32_e32 v20, 2.0, v231
	v_add_f32_e32 v21, 0x40400000, v231
	v_add_f32_e32 v22, 0x41000000, v231
	v_add_f32_e32 v23, 0x41100000, v231
	v_add_f32_e32 v24, 0x41200000, v231
	v_add_f32_e32 v25, 0x41300000, v231
	v_add_f32_e32 v26, 0x41800000, v231
	v_add_f32_e32 v27, 0x41880000, v231
	v_add_f32_e32 v28, 0x41900000, v231
	v_add_f32_e32 v29, 0x41980000, v231
	v_add_f32_e32 v30, 0x41c00000, v231
	v_add_f32_e32 v31, 0x41c80000, v231
	v_add_f32_e32 v32, 0x41d00000, v231
	v_add_f32_e32 v33, 0x41d80000, v231
	v_cmp_le_i32_e32 vcc, 0, v232
	v_cmp_ge_i32_e64 s[26:27], 0, v232
	v_cmp_le_i32_e64 s[2:3], 1, v232
	v_cndmask_b32_e32 v34, v226, v18, vcc
	v_cmp_ge_i32_e32 vcc, 1, v232
	v_cndmask_b32_e64 v50, v226, v18, s[26:27]
	v_cmp_le_i32_e64 s[26:27], 2, v232
	v_cndmask_b32_e64 v35, v226, v19, s[2:3]
	v_cmp_ge_i32_e64 s[2:3], 2, v232
	v_cndmask_b32_e32 v51, v226, v19, vcc
	v_cmp_le_i32_e32 vcc, 3, v232
	v_cndmask_b32_e64 v36, v226, v20, s[26:27]
	v_cmp_ge_i32_e64 s[26:27], 3, v232
	v_cndmask_b32_e64 v52, v226, v20, s[2:3]
	v_cmp_le_i32_e64 s[2:3], 8, v232
	v_cndmask_b32_e32 v37, v226, v21, vcc
	v_cmp_ge_i32_e32 vcc, 8, v232
	v_cndmask_b32_e64 v53, v226, v21, s[26:27]
	v_cmp_le_i32_e64 s[26:27], 9, v232
	v_cndmask_b32_e64 v38, v226, v22, s[2:3]
	v_cmp_ge_i32_e64 s[2:3], 9, v232
	v_cndmask_b32_e32 v54, v226, v22, vcc
	v_cmp_le_i32_e32 vcc, 10, v232
	v_cndmask_b32_e64 v39, v226, v23, s[26:27]
	v_cmp_ge_i32_e64 s[26:27], 10, v232
	v_cndmask_b32_e64 v55, v226, v23, s[2:3]
	v_cmp_le_i32_e64 s[2:3], 11, v232
	v_cndmask_b32_e32 v40, v226, v24, vcc
	v_cmp_ge_i32_e32 vcc, 11, v232
	v_cndmask_b32_e64 v56, v226, v24, s[26:27]
	v_cmp_le_i32_e64 s[26:27], 16, v232
	v_cndmask_b32_e64 v41, v226, v25, s[2:3]
	v_cmp_ge_i32_e64 s[2:3], 16, v232
	v_cndmask_b32_e32 v57, v226, v25, vcc
	v_cmp_le_i32_e32 vcc, 17, v232
	v_cndmask_b32_e64 v42, v226, v26, s[26:27]
	v_cmp_ge_i32_e64 s[26:27], 17, v232
	v_cndmask_b32_e64 v58, v226, v26, s[2:3]
	v_cmp_le_i32_e64 s[2:3], 18, v232
	v_cndmask_b32_e32 v43, v226, v27, vcc
	v_cmp_ge_i32_e32 vcc, 18, v232
	v_cndmask_b32_e64 v59, v226, v27, s[26:27]
	v_cmp_le_i32_e64 s[26:27], 19, v232
	v_cndmask_b32_e64 v44, v226, v28, s[2:3]
	v_cmp_ge_i32_e64 s[2:3], 19, v232
	v_cndmask_b32_e32 v60, v226, v28, vcc
	v_cmp_le_i32_e32 vcc, 24, v232
	v_cndmask_b32_e64 v45, v226, v29, s[26:27]
	v_cmp_ge_i32_e64 s[26:27], 24, v232
	v_cndmask_b32_e64 v61, v226, v29, s[2:3]
	v_cmp_le_i32_e64 s[2:3], 25, v232
	v_cndmask_b32_e32 v46, v226, v30, vcc
	v_cmp_ge_i32_e32 vcc, 25, v232
	v_cndmask_b32_e64 v62, v226, v30, s[26:27]
	v_cmp_le_i32_e64 s[26:27], 26, v232
	v_cndmask_b32_e64 v47, v226, v31, s[2:3]
	v_cmp_ge_i32_e64 s[2:3], 26, v232
	v_cndmask_b32_e32 v63, v226, v31, vcc
	v_cmp_le_i32_e32 vcc, 27, v232
	v_cndmask_b32_e64 v48, v226, v32, s[26:27]
	v_cmp_ge_i32_e64 s[26:27], 27, v232
	v_cndmask_b32_e64 v64, v226, v32, s[2:3]
	v_cndmask_b32_e32 v49, v226, v33, vcc
	v_cndmask_b32_e64 v65, v226, v33, s[26:27]
	s_branch .LBB0_755
